# candI + PEER step B loop: whole memory block (gather address math, 16 gathers, coef/h/id loads) hoisted to the top of each unrolled body, vmcnt re-derived
# baseline (speedup 1.0000x reference)
; __device__ __forceinline__ f32x2 fp8x2_lo(unsigned w) { return __builtin_amdgcn_cvt_pk_f32_fp8(w, false); }
; __device__ __forceinline__ f32x2 fp8x2_hi(unsigned w) { return __builtin_amdgcn_cvt_pk_f32_fp8(w, true); }
; #define PB_IDS(T) do { const unsigned* kp_ = KP + (size_t)(T) * 256; _Pragma("unroll") for (int qq = 0; qq < 4; ++qq) idv[qq] = *(const u32x4*)(kp_ + 4 * qq); } while (0)
; template <bool NT>
; __device__ __forceinline__ void peer_passB(const Args& a, const PeerWork w) {
;     ...
;     for (;; q += qs) {
;         u32x4 vrn[16]; f32x4 cfn[4]; f32x2 hn;
;         PB_GATHER(t1, vrn, cfn, hn);
;         const int t2 = peer_tok(w, min(q + 2 * qs, ql));
;         PB_IDS(t2);
;         f32x2 acc[8];
; #pragma unroll
;         for (int m = 0; m < 8; ++m) acc[m] = (f32x2){0.f, 0.f};
; #pragma unroll
;         for (int k = 0; k < 16; ++k) {
;             const unsigned ww[4] = {vr[k].x, vr[k].y, vr[k].z, vr[k].w};
;             const float c = cf[k >> 2][k & 3]; const f32x2 c2 = {c, c};
; #pragma unroll
;             for (int wd = 0; wd < 4; ++wd) { acc[2 * wd] = __builtin_elementwise_fma(fp8x2_lo(ww[wd]), c2, acc[2 * wd]); acc[2 * wd + 1] = __builtin_elementwise_fma(fp8x2_hi(ww[wd]), c2, acc[2 * wd + 1]); }
.LBB0_1587:
	s_waitcnt vmcnt(3)
	v_lshl_or_b32 v6, v6, 7, v1
	v_lshl_or_b32 v2, v2, 7, v1
	s_waitcnt vmcnt(1)
	v_lshl_or_b32 v14, v14, 7, v1
	v_lshl_or_b32 v10, v10, 7, v1
	global_load_dwordx4 v[106:109], v6, s[4:5]
	global_load_dwordx4 v[122:125], v2, s[4:5]
	v_lshl_or_b32 v6, v7, 7, v1
	v_lshl_or_b32 v2, v3, 7, v1
	s_mov_b32 s14, s6
	global_load_dwordx4 v[70:73], v14, s[4:5]
	global_load_dwordx4 v[86:89], v10, s[4:5]
	v_lshl_or_b32 v14, v15, 7, v1
	v_lshl_or_b32 v10, v11, 7, v1
	global_load_dwordx4 v[110:113], v6, s[4:5]
	global_load_dwordx4 v[126:129], v2, s[4:5]
	v_lshl_or_b32 v6, v8, 7, v1
	v_lshl_or_b32 v2, v4, 7, v1
	s_ashr_i32 s15, s6, 31
	global_load_dwordx4 v[74:77], v14, s[4:5]
	global_load_dwordx4 v[90:93], v10, s[4:5]
	v_lshl_or_b32 v14, v16, 7, v1
	v_lshl_or_b32 v10, v12, 7, v1
	global_load_dwordx4 v[114:117], v6, s[4:5]
	global_load_dwordx4 v[130:133], v2, s[4:5]
	v_lshl_or_b32 v6, v9, 7, v1
	v_lshl_or_b32 v2, v5, 7, v1
	s_lshl_b64 s[6:7], s[14:15], 9
	global_load_dwordx4 v[78:81], v14, s[4:5]
	global_load_dwordx4 v[98:101], v10, s[4:5]
	v_lshl_or_b32 v14, v17, 7, v1
	v_lshl_or_b32 v10, v13, 7, v1
	global_load_dwordx4 v[118:121], v6, s[4:5]
	global_load_dwordx4 v[134:137], v2, s[4:5]
	v_lshl_add_u64 v[2:3], v[184:185], 0, s[6:7]
	s_lshl_b64 s[6:7], s[14:15], 12
	global_load_dwordx4 v[82:85], v14, s[4:5]
	global_load_dwordx4 v[102:105], v10, s[4:5]
	global_load_dwordx4 v[142:145], v[2:3], off offset:48
	global_load_dwordx4 v[146:149], v[2:3], off offset:32
	global_load_dwordx4 v[150:153], v[2:3], off offset:16
	global_load_dwordx4 v[154:157], v[2:3], off
	v_lshl_add_u64 v[2:3], v[182:183], 0, s[6:7]
	s_add_i32 s6, s11, s18
	s_min_i32 s6, s6, 0x3fff
	s_ashr_i32 s7, s6, 31
	s_lshl_b64 s[28:29], s[6:7], 10
	v_lshl_add_u64 v[14:15], v[180:181], 0, s[28:29]
	global_load_dwordx2 v[188:189], v[2:3], off
	global_load_dwordx4 v[2:5], v[14:15], off offset:48
	global_load_dwordx4 v[6:9], v[14:15], off offset:32
	global_load_dwordx4 v[10:13], v[14:15], off offset:16
	global_load_dwordx4 v[14:17], v[14:15], off
	v_cvt_pk_f32_fp8_e32 v[192:193], v174
	v_cvt_pk_f32_fp8_e32 v[204:205], v170
	v_cvt_pk_f32_fp8_sdwa v[194:195], v174 src0_sel:WORD_1
	v_cvt_pk_f32_fp8_e32 v[196:197], v175
	v_pk_fma_f32 v[192:193], v[192:193], v[162:163], 0 op_sel_hi:[1,0,0]
	v_cvt_pk_f32_fp8_sdwa v[174:175], v175 src0_sel:WORD_1
	v_pk_fma_f32 v[192:193], v[204:205], v[162:163], v[192:193] op_sel:[0,1,0]
	v_cvt_pk_f32_fp8_sdwa v[204:205], v170 src0_sel:WORD_1
	v_pk_fma_f32 v[194:195], v[194:195], v[162:163], 0 op_sel_hi:[1,0,0]
	v_pk_fma_f32 v[174:175], v[174:175], v[162:163], 0 op_sel_hi:[1,0,0]
	v_cvt_pk_f32_fp8_e32 v[198:199], v176
	v_pk_fma_f32 v[194:195], v[204:205], v[162:163], v[194:195] op_sel:[0,1,0]
	v_cvt_pk_f32_fp8_e32 v[204:205], v171
	v_cvt_pk_f32_fp8_sdwa v[170:171], v171 src0_sel:WORD_1
	v_pk_fma_f32 v[198:199], v[198:199], v[162:163], 0 op_sel_hi:[1,0,0]
	v_cvt_pk_f32_fp8_sdwa v[200:201], v176 src0_sel:WORD_1
	v_cvt_pk_f32_fp8_e32 v[202:203], v177
	v_pk_fma_f32 v[170:171], v[170:171], v[162:163], v[174:175] op_sel:[0,1,0]
	v_cvt_pk_f32_fp8_e32 v[174:175], v172
	v_pk_fma_f32 v[200:201], v[200:201], v[162:163], 0 op_sel_hi:[1,0,0]
	v_cvt_pk_f32_fp8_sdwa v[176:177], v177 src0_sel:WORD_1
	v_pk_fma_f32 v[196:197], v[196:197], v[162:163], 0 op_sel_hi:[1,0,0]
	v_pk_fma_f32 v[174:175], v[174:175], v[162:163], v[198:199] op_sel:[0,1,0]
	v_cvt_pk_f32_fp8_sdwa v[198:199], v172 src0_sel:WORD_1
	v_pk_fma_f32 v[202:203], v[202:203], v[162:163], 0 op_sel_hi:[1,0,0]
	v_pk_fma_f32 v[176:177], v[176:177], v[162:163], 0 op_sel_hi:[1,0,0]
	v_pk_fma_f32 v[196:197], v[204:205], v[162:163], v[196:197] op_sel:[0,1,0]
	v_pk_fma_f32 v[198:199], v[198:199], v[162:163], v[200:201] op_sel:[0,1,0]
	v_cvt_pk_f32_fp8_e32 v[200:201], v173
	v_cvt_pk_f32_fp8_sdwa v[172:173], v173 src0_sel:WORD_1
	v_pk_fma_f32 v[200:201], v[200:201], v[162:163], v[202:203] op_sel:[0,1,0]
	v_pk_fma_f32 v[162:163], v[172:173], v[162:163], v[176:177] op_sel:[0,1,0]
	v_cvt_pk_f32_fp8_e32 v[172:173], v166
	v_cvt_pk_f32_fp8_sdwa v[176:177], v166 src0_sel:WORD_1
	v_pk_fma_f32 v[172:173], v[172:173], v[164:165], v[192:193] op_sel_hi:[1,0,1]
	v_cvt_pk_f32_fp8_e32 v[192:193], v167
	v_cvt_pk_f32_fp8_sdwa v[166:167], v167 src0_sel:WORD_1
	v_pk_fma_f32 v[176:177], v[176:177], v[164:165], v[194:195] op_sel_hi:[1,0,1]
	v_cvt_pk_f32_fp8_e32 v[194:195], v169
	v_pk_fma_f32 v[192:193], v[192:193], v[164:165], v[196:197] op_sel_hi:[1,0,1]
	v_pk_fma_f32 v[166:167], v[166:167], v[164:165], v[170:171] op_sel_hi:[1,0,1]
	v_cvt_pk_f32_fp8_e32 v[170:171], v168
	v_pk_fma_f32 v[194:195], v[194:195], v[164:165], v[200:201] op_sel_hi:[1,0,1]
	v_pk_fma_f32 v[170:171], v[170:171], v[164:165], v[174:175] op_sel_hi:[1,0,1]
	v_cvt_pk_f32_fp8_sdwa v[174:175], v168 src0_sel:WORD_1
	v_cvt_pk_f32_fp8_sdwa v[168:169], v169 src0_sel:WORD_1
	v_pk_fma_f32 v[174:175], v[174:175], v[164:165], v[198:199] op_sel_hi:[1,0,1]
	v_pk_fma_f32 v[162:163], v[168:169], v[164:165], v[162:163] op_sel_hi:[1,0,1]
	v_cvt_pk_f32_fp8_e32 v[168:169], v158
	v_mov_b32_e32 v164, v165
	v_pk_fma_f32 v[168:169], v[168:169], v[164:165], v[172:173] op_sel_hi:[1,0,1]
	v_cvt_pk_f32_fp8_sdwa v[172:173], v158 src0_sel:WORD_1
	v_pk_fma_f32 v[172:173], v[172:173], v[164:165], v[176:177] op_sel_hi:[1,0,1]
	v_cvt_pk_f32_fp8_e32 v[176:177], v159
	v_cvt_pk_f32_fp8_sdwa v[158:159], v159 src0_sel:WORD_1
	v_pk_fma_f32 v[176:177], v[176:177], v[164:165], v[192:193] op_sel_hi:[1,0,1]
	v_pk_fma_f32 v[158:159], v[158:159], v[164:165], v[166:167] op_sel_hi:[1,0,1]
	v_cvt_pk_f32_fp8_e32 v[166:167], v160
	v_pk_fma_f32 v[166:167], v[166:167], v[164:165], v[170:171] op_sel_hi:[1,0,1]
; __device__ __forceinline__ f32x2 fp8x2_lo(unsigned w) { return __builtin_amdgcn_cvt_pk_f32_fp8(w, false); }
; __device__ __forceinline__ f32x2 fp8x2_hi(unsigned w) { return __builtin_amdgcn_cvt_pk_f32_fp8(w, true); }
; template <bool NT>
; __device__ __forceinline__ void peer_passB(const Args& a, const PeerWork w) {
;     ...
; #pragma unroll
;         for (int m = 0; m < 8; ++m) acc[m] = (f32x2){0.f, 0.f};
; #pragma unroll
;         for (int k = 0; k < 16; ++k) {
;             const unsigned ww[4] = {vr[k].x, vr[k].y, vr[k].z, vr[k].w};
;             const float c = cf[k >> 2][k & 3]; const f32x2 c2 = {c, c};
; #pragma unroll
;             for (int wd = 0; wd < 4; ++wd) { acc[2 * wd] = __builtin_elementwise_fma(fp8x2_lo(ww[wd]), c2, acc[2 * wd]); acc[2 * wd + 1] = __builtin_elementwise_fma(fp8x2_hi(ww[wd]), c2, acc[2 * wd + 1]); }
;         }
	v_cvt_pk_f32_fp8_sdwa v[170:171], v160 src0_sel:WORD_1
	v_pk_fma_f32 v[170:171], v[170:171], v[164:165], v[174:175] op_sel_hi:[1,0,1]
	v_cvt_pk_f32_fp8_e32 v[174:175], v161
	v_cvt_pk_f32_fp8_sdwa v[160:161], v161 src0_sel:WORD_1
	v_pk_fma_f32 v[174:175], v[174:175], v[164:165], v[194:195] op_sel_hi:[1,0,1]
	v_pk_fma_f32 v[160:161], v[160:161], v[164:165], v[162:163] op_sel_hi:[1,0,1]
	v_cvt_pk_f32_fp8_e32 v[162:163], v138
	v_cvt_pk_f32_fp8_sdwa v[164:165], v138 src0_sel:WORD_1
	v_pk_fma_f32 v[162:163], v[162:163], v[62:63], v[168:169] op_sel_hi:[1,0,1]
	v_cvt_pk_f32_fp8_e32 v[168:169], v139
	v_cvt_pk_f32_fp8_sdwa v[138:139], v139 src0_sel:WORD_1
	v_pk_fma_f32 v[164:165], v[164:165], v[62:63], v[172:173] op_sel_hi:[1,0,1]
	v_pk_fma_f32 v[168:169], v[168:169], v[62:63], v[176:177] op_sel_hi:[1,0,1]
	v_pk_fma_f32 v[138:139], v[138:139], v[62:63], v[158:159] op_sel_hi:[1,0,1]
	v_cvt_pk_f32_fp8_e32 v[158:159], v140
	v_pk_fma_f32 v[158:159], v[158:159], v[62:63], v[166:167] op_sel_hi:[1,0,1]
	v_cvt_pk_f32_fp8_sdwa v[166:167], v140 src0_sel:WORD_1
	v_pk_fma_f32 v[166:167], v[166:167], v[62:63], v[170:171] op_sel_hi:[1,0,1]
	v_cvt_pk_f32_fp8_e32 v[170:171], v141
	v_cvt_pk_f32_fp8_sdwa v[140:141], v141 src0_sel:WORD_1
	v_pk_fma_f32 v[170:171], v[170:171], v[62:63], v[174:175] op_sel_hi:[1,0,1]
	v_pk_fma_f32 v[140:141], v[140:141], v[62:63], v[160:161] op_sel_hi:[1,0,1]
	v_cvt_pk_f32_fp8_e32 v[160:161], v94
	v_pk_fma_f32 v[160:161], v[160:161], v[62:63], v[162:163] op_sel:[0,1,0]
	v_cvt_pk_f32_fp8_sdwa v[162:163], v94 src0_sel:WORD_1
	v_pk_fma_f32 v[162:163], v[162:163], v[62:63], v[164:165] op_sel:[0,1,0]
	v_cvt_pk_f32_fp8_e32 v[164:165], v95
	v_cvt_pk_f32_fp8_sdwa v[94:95], v95 src0_sel:WORD_1
	s_ashr_i32 s13, s12, 31
	v_pk_fma_f32 v[164:165], v[164:165], v[62:63], v[168:169] op_sel:[0,1,0]
	v_pk_fma_f32 v[94:95], v[94:95], v[62:63], v[138:139] op_sel:[0,1,0]
	v_cvt_pk_f32_fp8_e32 v[138:139], v96
	s_lshl_b64 s[12:13], s[12:13], 12
	s_add_i32 s18, s18, s22
	v_pk_fma_f32 v[138:139], v[138:139], v[62:63], v[158:159] op_sel:[0,1,0]
	v_cvt_pk_f32_fp8_sdwa v[158:159], v96 src0_sel:WORD_1
	s_cmpk_lt_i32 s18, 0x4000
	v_pk_fma_f32 v[158:159], v[158:159], v[62:63], v[166:167] op_sel:[0,1,0]
	v_cvt_pk_f32_fp8_e32 v[166:167], v97
	v_cvt_pk_f32_fp8_sdwa v[96:97], v97 src0_sel:WORD_1
	v_pk_fma_f32 v[166:167], v[166:167], v[62:63], v[170:171] op_sel:[0,1,0]
	v_pk_fma_f32 v[62:63], v[96:97], v[62:63], v[140:141] op_sel:[0,1,0]
	v_cvt_pk_f32_fp8_e32 v[96:97], v66
	v_cvt_pk_f32_fp8_sdwa v[140:141], v66 src0_sel:WORD_1
	v_pk_fma_f32 v[96:97], v[96:97], v[64:65], v[160:161] op_sel_hi:[1,0,1]
	v_cvt_pk_f32_fp8_e32 v[160:161], v67
	v_cvt_pk_f32_fp8_sdwa v[66:67], v67 src0_sel:WORD_1
	v_pk_fma_f32 v[140:141], v[140:141], v[64:65], v[162:163] op_sel_hi:[1,0,1]
	v_pk_fma_f32 v[160:161], v[160:161], v[64:65], v[164:165] op_sel_hi:[1,0,1]
	v_pk_fma_f32 v[66:67], v[66:67], v[64:65], v[94:95] op_sel_hi:[1,0,1]
	v_cvt_pk_f32_fp8_e32 v[94:95], v68
	v_pk_fma_f32 v[94:95], v[94:95], v[64:65], v[138:139] op_sel_hi:[1,0,1]
	v_cvt_pk_f32_fp8_sdwa v[138:139], v68 src0_sel:WORD_1
	v_pk_fma_f32 v[138:139], v[138:139], v[64:65], v[158:159] op_sel_hi:[1,0,1]
	v_cvt_pk_f32_fp8_e32 v[158:159], v69
	v_cvt_pk_f32_fp8_sdwa v[68:69], v69 src0_sel:WORD_1
	v_pk_fma_f32 v[158:159], v[158:159], v[64:65], v[166:167] op_sel_hi:[1,0,1]
	v_pk_fma_f32 v[62:63], v[68:69], v[64:65], v[62:63] op_sel_hi:[1,0,1]
	v_cvt_pk_f32_fp8_e32 v[68:69], v58
	v_mov_b32_e32 v64, v65
	v_pk_fma_f32 v[68:69], v[68:69], v[64:65], v[96:97] op_sel_hi:[1,0,1]
	v_cvt_pk_f32_fp8_sdwa v[96:97], v58 src0_sel:WORD_1
	v_pk_fma_f32 v[96:97], v[96:97], v[64:65], v[140:141] op_sel_hi:[1,0,1]
	v_cvt_pk_f32_fp8_e32 v[140:141], v59
	v_cvt_pk_f32_fp8_sdwa v[58:59], v59 src0_sel:WORD_1
	v_pk_fma_f32 v[140:141], v[140:141], v[64:65], v[160:161] op_sel_hi:[1,0,1]
	v_pk_fma_f32 v[58:59], v[58:59], v[64:65], v[66:67] op_sel_hi:[1,0,1]
	v_cvt_pk_f32_fp8_e32 v[66:67], v60
	v_pk_fma_f32 v[66:67], v[66:67], v[64:65], v[94:95] op_sel_hi:[1,0,1]
	v_cvt_pk_f32_fp8_sdwa v[94:95], v60 src0_sel:WORD_1
	v_pk_fma_f32 v[94:95], v[94:95], v[64:65], v[138:139] op_sel_hi:[1,0,1]
	v_cvt_pk_f32_fp8_e32 v[138:139], v61
	v_cvt_pk_f32_fp8_sdwa v[60:61], v61 src0_sel:WORD_1
	v_pk_fma_f32 v[138:139], v[138:139], v[64:65], v[158:159] op_sel_hi:[1,0,1]
	v_pk_fma_f32 v[60:61], v[60:61], v[64:65], v[62:63] op_sel_hi:[1,0,1]
	v_cvt_pk_f32_fp8_e32 v[62:63], v54
	v_cvt_pk_f32_fp8_sdwa v[64:65], v54 src0_sel:WORD_1
	v_pk_fma_f32 v[62:63], v[62:63], v[38:39], v[68:69] op_sel_hi:[1,0,1]
	v_cvt_pk_f32_fp8_e32 v[68:69], v55
	v_cvt_pk_f32_fp8_sdwa v[54:55], v55 src0_sel:WORD_1
	v_pk_fma_f32 v[64:65], v[64:65], v[38:39], v[96:97] op_sel_hi:[1,0,1]
	v_pk_fma_f32 v[68:69], v[68:69], v[38:39], v[140:141] op_sel_hi:[1,0,1]
	v_pk_fma_f32 v[54:55], v[54:55], v[38:39], v[58:59] op_sel_hi:[1,0,1]
	v_cvt_pk_f32_fp8_e32 v[58:59], v56
	v_pk_fma_f32 v[58:59], v[58:59], v[38:39], v[66:67] op_sel_hi:[1,0,1]
	v_cvt_pk_f32_fp8_sdwa v[66:67], v56 src0_sel:WORD_1
	v_pk_fma_f32 v[66:67], v[66:67], v[38:39], v[94:95] op_sel_hi:[1,0,1]
	v_cvt_pk_f32_fp8_e32 v[94:95], v57
	v_cvt_pk_f32_fp8_sdwa v[56:57], v57 src0_sel:WORD_1
	v_pk_fma_f32 v[94:95], v[94:95], v[38:39], v[138:139] op_sel_hi:[1,0,1]
	v_pk_fma_f32 v[56:57], v[56:57], v[38:39], v[60:61] op_sel_hi:[1,0,1]
	v_cvt_pk_f32_fp8_e32 v[60:61], v50
	v_pk_fma_f32 v[60:61], v[60:61], v[38:39], v[62:63] op_sel:[0,1,0]
	v_cvt_pk_f32_fp8_sdwa v[62:63], v50 src0_sel:WORD_1
	v_pk_fma_f32 v[62:63], v[62:63], v[38:39], v[64:65] op_sel:[0,1,0]
	v_cvt_pk_f32_fp8_e32 v[64:65], v51
	v_cvt_pk_f32_fp8_sdwa v[50:51], v51 src0_sel:WORD_1
; __device__ __forceinline__ f32x2 fp8x2_lo(unsigned w) { return __builtin_amdgcn_cvt_pk_f32_fp8(w, false); }
; __device__ __forceinline__ f32x2 fp8x2_hi(unsigned w) { return __builtin_amdgcn_cvt_pk_f32_fp8(w, true); }
; template <bool NT>
; __device__ __forceinline__ void peer_passB(const Args& a, const PeerWork w) {
;     ...
;         for (int k = 0; k < 16; ++k) {
;             const unsigned ww[4] = {vr[k].x, vr[k].y, vr[k].z, vr[k].w};
;             const float c = cf[k >> 2][k & 3]; const f32x2 c2 = {c, c};
; #pragma unroll
;             for (int wd = 0; wd < 4; ++wd) { acc[2 * wd] = __builtin_elementwise_fma(fp8x2_lo(ww[wd]), c2, acc[2 * wd]); acc[2 * wd + 1] = __builtin_elementwise_fma(fp8x2_hi(ww[wd]), c2, acc[2 * wd + 1]); }
	v_pk_fma_f32 v[64:65], v[64:65], v[38:39], v[68:69] op_sel:[0,1,0]
	v_pk_fma_f32 v[50:51], v[50:51], v[38:39], v[54:55] op_sel:[0,1,0]
	v_cvt_pk_f32_fp8_e32 v[54:55], v52
	v_pk_fma_f32 v[54:55], v[54:55], v[38:39], v[58:59] op_sel:[0,1,0]
	v_cvt_pk_f32_fp8_sdwa v[58:59], v52 src0_sel:WORD_1
	v_pk_fma_f32 v[58:59], v[58:59], v[38:39], v[66:67] op_sel:[0,1,0]
	v_cvt_pk_f32_fp8_e32 v[66:67], v53
	v_cvt_pk_f32_fp8_sdwa v[52:53], v53 src0_sel:WORD_1
	v_pk_fma_f32 v[66:67], v[66:67], v[38:39], v[94:95] op_sel:[0,1,0]
	v_pk_fma_f32 v[38:39], v[52:53], v[38:39], v[56:57] op_sel:[0,1,0]
	v_cvt_pk_f32_fp8_e32 v[52:53], v46
	v_cvt_pk_f32_fp8_sdwa v[56:57], v46 src0_sel:WORD_1
	v_pk_fma_f32 v[52:53], v[52:53], v[40:41], v[60:61] op_sel_hi:[1,0,1]
	v_cvt_pk_f32_fp8_e32 v[60:61], v47
	v_cvt_pk_f32_fp8_sdwa v[46:47], v47 src0_sel:WORD_1
	v_pk_fma_f32 v[56:57], v[56:57], v[40:41], v[62:63] op_sel_hi:[1,0,1]
	v_pk_fma_f32 v[60:61], v[60:61], v[40:41], v[64:65] op_sel_hi:[1,0,1]
	v_pk_fma_f32 v[46:47], v[46:47], v[40:41], v[50:51] op_sel_hi:[1,0,1]
	v_cvt_pk_f32_fp8_e32 v[50:51], v48
	v_pk_fma_f32 v[50:51], v[50:51], v[40:41], v[54:55] op_sel_hi:[1,0,1]
	v_cvt_pk_f32_fp8_sdwa v[54:55], v48 src0_sel:WORD_1
	v_pk_fma_f32 v[54:55], v[54:55], v[40:41], v[58:59] op_sel_hi:[1,0,1]
	v_cvt_pk_f32_fp8_e32 v[58:59], v49
	v_cvt_pk_f32_fp8_sdwa v[48:49], v49 src0_sel:WORD_1
	v_pk_fma_f32 v[58:59], v[58:59], v[40:41], v[66:67] op_sel_hi:[1,0,1]
	v_pk_fma_f32 v[38:39], v[48:49], v[40:41], v[38:39] op_sel_hi:[1,0,1]
	v_cvt_pk_f32_fp8_e32 v[48:49], v42
	v_mov_b32_e32 v40, v41
	v_pk_fma_f32 v[48:49], v[48:49], v[40:41], v[52:53] op_sel_hi:[1,0,1]
	v_cvt_pk_f32_fp8_sdwa v[52:53], v42 src0_sel:WORD_1
	v_pk_fma_f32 v[52:53], v[52:53], v[40:41], v[56:57] op_sel_hi:[1,0,1]
	v_cvt_pk_f32_fp8_e32 v[56:57], v43
	v_cvt_pk_f32_fp8_sdwa v[42:43], v43 src0_sel:WORD_1
	v_pk_fma_f32 v[56:57], v[56:57], v[40:41], v[60:61] op_sel_hi:[1,0,1]
	v_pk_fma_f32 v[42:43], v[42:43], v[40:41], v[46:47] op_sel_hi:[1,0,1]
	v_cvt_pk_f32_fp8_e32 v[46:47], v44
	v_pk_fma_f32 v[46:47], v[46:47], v[40:41], v[50:51] op_sel_hi:[1,0,1]
	v_cvt_pk_f32_fp8_sdwa v[50:51], v44 src0_sel:WORD_1
	v_pk_fma_f32 v[50:51], v[50:51], v[40:41], v[54:55] op_sel_hi:[1,0,1]
	v_cvt_pk_f32_fp8_e32 v[54:55], v45
	v_cvt_pk_f32_fp8_sdwa v[44:45], v45 src0_sel:WORD_1
	v_pk_fma_f32 v[54:55], v[54:55], v[40:41], v[58:59] op_sel_hi:[1,0,1]
	v_pk_fma_f32 v[38:39], v[44:45], v[40:41], v[38:39] op_sel_hi:[1,0,1]
	v_cvt_pk_f32_fp8_e32 v[40:41], v34
	v_cvt_pk_f32_fp8_sdwa v[44:45], v34 src0_sel:WORD_1
	v_pk_fma_f32 v[40:41], v[40:41], v[22:23], v[48:49] op_sel_hi:[1,0,1]
	v_cvt_pk_f32_fp8_e32 v[48:49], v35
	v_cvt_pk_f32_fp8_sdwa v[34:35], v35 src0_sel:WORD_1
	v_pk_fma_f32 v[44:45], v[44:45], v[22:23], v[52:53] op_sel_hi:[1,0,1]
	v_pk_fma_f32 v[48:49], v[48:49], v[22:23], v[56:57] op_sel_hi:[1,0,1]
	v_pk_fma_f32 v[34:35], v[34:35], v[22:23], v[42:43] op_sel_hi:[1,0,1]
	v_cvt_pk_f32_fp8_e32 v[42:43], v36
	v_pk_fma_f32 v[42:43], v[42:43], v[22:23], v[46:47] op_sel_hi:[1,0,1]
	v_cvt_pk_f32_fp8_sdwa v[46:47], v36 src0_sel:WORD_1
	v_pk_fma_f32 v[46:47], v[46:47], v[22:23], v[50:51] op_sel_hi:[1,0,1]
	v_cvt_pk_f32_fp8_e32 v[50:51], v37
	v_cvt_pk_f32_fp8_sdwa v[36:37], v37 src0_sel:WORD_1
	v_pk_fma_f32 v[50:51], v[50:51], v[22:23], v[54:55] op_sel_hi:[1,0,1]
	v_pk_fma_f32 v[36:37], v[36:37], v[22:23], v[38:39] op_sel_hi:[1,0,1]
	v_cvt_pk_f32_fp8_e32 v[38:39], v30
	v_pk_fma_f32 v[38:39], v[38:39], v[22:23], v[40:41] op_sel:[0,1,0]
	v_cvt_pk_f32_fp8_sdwa v[40:41], v30 src0_sel:WORD_1
	v_pk_fma_f32 v[40:41], v[40:41], v[22:23], v[44:45] op_sel:[0,1,0]
	v_cvt_pk_f32_fp8_e32 v[44:45], v31
	v_cvt_pk_f32_fp8_sdwa v[30:31], v31 src0_sel:WORD_1
	v_pk_fma_f32 v[44:45], v[44:45], v[22:23], v[48:49] op_sel:[0,1,0]
	v_pk_fma_f32 v[30:31], v[30:31], v[22:23], v[34:35] op_sel:[0,1,0]
	v_cvt_pk_f32_fp8_e32 v[34:35], v32
	v_pk_fma_f32 v[34:35], v[34:35], v[22:23], v[42:43] op_sel:[0,1,0]
	v_cvt_pk_f32_fp8_sdwa v[42:43], v32 src0_sel:WORD_1
	v_pk_fma_f32 v[42:43], v[42:43], v[22:23], v[46:47] op_sel:[0,1,0]
	v_cvt_pk_f32_fp8_e32 v[46:47], v33
	v_cvt_pk_f32_fp8_sdwa v[32:33], v33 src0_sel:WORD_1
	v_pk_fma_f32 v[46:47], v[46:47], v[22:23], v[50:51] op_sel:[0,1,0]
	v_pk_fma_f32 v[22:23], v[32:33], v[22:23], v[36:37] op_sel:[0,1,0]
	v_cvt_pk_f32_fp8_e32 v[32:33], v26
	v_cvt_pk_f32_fp8_sdwa v[36:37], v26 src0_sel:WORD_1
	v_pk_fma_f32 v[32:33], v[32:33], v[24:25], v[38:39] op_sel_hi:[1,0,1]
	v_cvt_pk_f32_fp8_e32 v[38:39], v27
	v_cvt_pk_f32_fp8_sdwa v[26:27], v27 src0_sel:WORD_1
	v_pk_fma_f32 v[36:37], v[36:37], v[24:25], v[40:41] op_sel_hi:[1,0,1]
	v_cvt_pk_f32_fp8_e32 v[40:41], v29
	v_pk_fma_f32 v[38:39], v[38:39], v[24:25], v[44:45] op_sel_hi:[1,0,1]
	v_pk_fma_f32 v[26:27], v[26:27], v[24:25], v[30:31] op_sel_hi:[1,0,1]
	v_cvt_pk_f32_fp8_e32 v[30:31], v28
	v_pk_fma_f32 v[40:41], v[40:41], v[24:25], v[46:47] op_sel_hi:[1,0,1]
	v_pk_fma_f32 v[30:31], v[30:31], v[24:25], v[34:35] op_sel_hi:[1,0,1]
	v_cvt_pk_f32_fp8_sdwa v[34:35], v28 src0_sel:WORD_1
	v_cvt_pk_f32_fp8_sdwa v[28:29], v29 src0_sel:WORD_1
	v_pk_fma_f32 v[34:35], v[34:35], v[24:25], v[42:43] op_sel_hi:[1,0,1]
	v_pk_fma_f32 v[22:23], v[28:29], v[24:25], v[22:23] op_sel_hi:[1,0,1]
	v_cvt_pk_f32_fp8_e32 v[28:29], v18
	v_mov_b32_e32 v24, v25
	v_pk_fma_f32 v[28:29], v[28:29], v[24:25], v[32:33] op_sel_hi:[1,0,1]
	v_cvt_pk_f32_fp8_sdwa v[32:33], v18 src0_sel:WORD_1
	v_pk_fma_f32 v[32:33], v[32:33], v[24:25], v[36:37] op_sel_hi:[1,0,1]
	v_cvt_pk_f32_fp8_e32 v[36:37], v19
	v_cvt_pk_f32_fp8_sdwa v[18:19], v19 src0_sel:WORD_1
	v_pk_fma_f32 v[36:37], v[36:37], v[24:25], v[38:39] op_sel_hi:[1,0,1]
; template <int CTRL> __device__ __forceinline__ float dpp_f(float x) { return __uint_as_float((unsigned)__builtin_amdgcn_update_dpp(0, (int)__float_as_uint(x), CTRL, 0xf, 0xf, false)); }
; __device__ __forceinline__ f32x2 fp8x2_lo(unsigned w) { return __builtin_amdgcn_cvt_pk_f32_fp8(w, false); }
; __device__ __forceinline__ f32x2 fp8x2_hi(unsigned w) { return __builtin_amdgcn_cvt_pk_f32_fp8(w, true); }
; #define PB_IDS(T) do { const unsigned* kp_ = KP + (size_t)(T) * 256; _Pragma("unroll") for (int qq = 0; qq < 4; ++qq) idv[qq] = *(const u32x4*)(kp_ + 4 * qq); } while (0)
; template <bool NT>
; __device__ __forceinline__ void peer_passB(const Args& a, const PeerWork w) {
;     ...
;     for (;; q += qs) {
;         u32x4 vrn[16]; f32x4 cfn[4]; f32x2 hn;
;         PB_GATHER(t1, vrn, cfn, hn);
;         const int t2 = peer_tok(w, min(q + 2 * qs, ql));
;         PB_IDS(t2);
;         f32x2 acc[8];
; #pragma unroll
;         for (int m = 0; m < 8; ++m) acc[m] = (f32x2){0.f, 0.f};
; #pragma unroll
;         for (int k = 0; k < 16; ++k) {
;             const unsigned ww[4] = {vr[k].x, vr[k].y, vr[k].z, vr[k].w};
;             const float c = cf[k >> 2][k & 3]; const f32x2 c2 = {c, c};
; #pragma unroll
;             for (int wd = 0; wd < 4; ++wd) { acc[2 * wd] = __builtin_elementwise_fma(fp8x2_lo(ww[wd]), c2, acc[2 * wd]); acc[2 * wd + 1] = __builtin_elementwise_fma(fp8x2_hi(ww[wd]), c2, acc[2 * wd + 1]); }
;     ...
;         float w8[8], w4[4], w2[2];
; #pragma unroll
;         for (int m = 0; m < 8; ++m) { const auto sw = __builtin_amdgcn_permlane32_swap(__float_as_uint(acc[m >> 1][m & 1]), __float_as_uint(acc[(m + 8) >> 1][m & 1]), false, false); w8[m] = __uint_as_float(sw[0]) + __uint_as_float(sw[1]); }
; #pragma unroll
;         for (int m = 0; m < 4; ++m) { const auto sw = __builtin_amdgcn_permlane16_swap(__float_as_uint(w8[m]), __float_as_uint(w8[m + 4]), false, false); w4[m] = __uint_as_float(sw[0]) + __uint_as_float(sw[1]); }
;         { const bool up = (lane & 8) != 0;
; #pragma unroll
;           for (int m = 0; m < 2; ++m) { const float keep = up ? w4[m + 2] : w4[m], send = up ? w4[m] : w4[m + 2]; w2[m] = keep + dpp_f<0x128>(send); } }
;         *(f32x2*)(Y + (size_t)t * DM) = (f32x2){hv[0] + w2[0], hv[1] + w2[1]};
	v_pk_fma_f32 v[18:19], v[18:19], v[24:25], v[26:27] op_sel_hi:[1,0,1]
	v_cvt_pk_f32_fp8_e32 v[26:27], v20
	v_pk_fma_f32 v[26:27], v[26:27], v[24:25], v[30:31] op_sel_hi:[1,0,1]
	v_cvt_pk_f32_fp8_sdwa v[30:31], v20 src0_sel:WORD_1
	s_nop 0
	v_permlane32_swap_b32_e32 v28, v26
	v_permlane32_swap_b32_e32 v29, v27
	v_pk_fma_f32 v[30:31], v[30:31], v[24:25], v[34:35] op_sel_hi:[1,0,1]
	v_cvt_pk_f32_fp8_e32 v[34:35], v21
	v_cvt_pk_f32_fp8_sdwa v[20:21], v21 src0_sel:WORD_1
	v_permlane32_swap_b32_e32 v32, v30
	v_pk_fma_f32 v[34:35], v[34:35], v[24:25], v[40:41] op_sel_hi:[1,0,1]
	v_pk_fma_f32 v[20:21], v[20:21], v[24:25], v[22:23] op_sel_hi:[1,0,1]
	v_permlane32_swap_b32_e32 v33, v31
	v_permlane32_swap_b32_e32 v36, v34
	v_permlane32_swap_b32_e32 v37, v35
	v_permlane32_swap_b32_e32 v18, v20
	v_permlane32_swap_b32_e32 v19, v21
	v_add_f32_e32 v22, v28, v26
	v_add_f32_e32 v23, v29, v27
	v_add_f32_e32 v24, v32, v30
	v_add_f32_e32 v25, v33, v31
	v_add_f32_e32 v26, v36, v34
	v_add_f32_e32 v27, v37, v35
	v_add_f32_e32 v18, v18, v20
	v_add_f32_e32 v19, v19, v21
	v_permlane16_swap_b32_e32 v22, v26
	v_permlane16_swap_b32_e32 v23, v27
	v_permlane16_swap_b32_e32 v24, v18
	v_permlane16_swap_b32_e32 v25, v19
	v_pk_add_f32 v[20:21], v[22:23], v[26:27]
	v_pk_add_f32 v[18:19], v[24:25], v[18:19]
	v_mov_b32_e32 v22, 0
	v_cndmask_b32_e32 v23, v20, v18, vcc
	v_cndmask_b32_e32 v24, v18, v20, vcc
	v_cndmask_b32_e32 v18, v21, v19, vcc
	v_mov_b32_dpp v22, v23 row_ror:8 row_mask:0xf bank_mask:0xf
	v_mov_b32_e32 v23, 0
	v_cndmask_b32_e32 v25, v19, v21, vcc
	v_lshl_add_u64 v[20:21], v[186:187], 0, s[12:13]
	v_mov_b32_dpp v23, v18 row_ror:8 row_mask:0xf bank_mask:0xf
	v_pk_add_f32 v[18:19], v[24:25], v[22:23]
	v_pk_add_f32 v[18:19], v[190:191], v[18:19]
	global_store_dwordx2 v[20:21], v[18:19], off
	s_mov_b32 s12, s14
	s_cbranch_scc0 .LBB0_1588
	s_waitcnt vmcnt(3)
	v_lshl_or_b32 v6, v6, 7, v1
	v_lshl_or_b32 v2, v2, 7, v1
	s_waitcnt vmcnt(1)
	v_lshl_or_b32 v14, v14, 7, v1
	v_lshl_or_b32 v10, v10, 7, v1
	global_load_dwordx4 v[54:57], v6, s[4:5]
	global_load_dwordx4 v[34:37], v2, s[4:5]
	v_lshl_or_b32 v6, v7, 7, v1
	v_lshl_or_b32 v2, v3, 7, v1
	s_mov_b32 s14, s6
	global_load_dwordx4 v[174:177], v14, s[4:5]
	global_load_dwordx4 v[138:141], v10, s[4:5]
	v_lshl_or_b32 v14, v15, 7, v1
	v_lshl_or_b32 v10, v11, 7, v1
	global_load_dwordx4 v[50:53], v6, s[4:5]
	global_load_dwordx4 v[30:33], v2, s[4:5]
	v_lshl_or_b32 v6, v8, 7, v1
	v_lshl_or_b32 v2, v4, 7, v1
	s_ashr_i32 s15, s6, 31
	global_load_dwordx4 v[170:173], v14, s[4:5]
	global_load_dwordx4 v[94:97], v10, s[4:5]
	v_lshl_or_b32 v14, v16, 7, v1
	v_lshl_or_b32 v10, v12, 7, v1
	global_load_dwordx4 v[46:49], v6, s[4:5]
	global_load_dwordx4 v[26:29], v2, s[4:5]
	v_lshl_or_b32 v6, v9, 7, v1
	v_lshl_or_b32 v2, v5, 7, v1
	s_lshl_b64 s[6:7], s[14:15], 9
	global_load_dwordx4 v[166:169], v14, s[4:5]
	global_load_dwordx4 v[66:69], v10, s[4:5]
	v_lshl_or_b32 v14, v17, 7, v1
	v_lshl_or_b32 v10, v13, 7, v1
	global_load_dwordx4 v[42:45], v6, s[4:5]
	global_load_dwordx4 v[18:21], v2, s[4:5]
	v_lshl_add_u64 v[2:3], v[184:185], 0, s[6:7]
	s_lshl_b64 s[6:7], s[14:15], 12
	global_load_dwordx4 v[158:161], v14, s[4:5]
	global_load_dwordx4 v[58:61], v10, s[4:5]
	global_load_dwordx4 v[22:25], v[2:3], off offset:48
	global_load_dwordx4 v[38:41], v[2:3], off offset:32
	global_load_dwordx4 v[62:65], v[2:3], off offset:16
	global_load_dwordx4 v[162:165], v[2:3], off
	v_lshl_add_u64 v[2:3], v[182:183], 0, s[6:7]
	s_add_i32 s6, s11, s18
	s_min_i32 s6, s6, 0x3fff
	s_ashr_i32 s7, s6, 31
	s_lshl_b64 s[28:29], s[6:7], 10
	v_lshl_add_u64 v[14:15], v[180:181], 0, s[28:29]
	global_load_dwordx2 v[190:191], v[2:3], off
	global_load_dwordx4 v[2:5], v[14:15], off offset:48
	global_load_dwordx4 v[6:9], v[14:15], off offset:32
	global_load_dwordx4 v[10:13], v[14:15], off offset:16
	global_load_dwordx4 v[14:17], v[14:15], off
	v_cvt_pk_f32_fp8_e32 v[192:193], v70
	v_cvt_pk_f32_fp8_e32 v[204:205], v74
	v_cvt_pk_f32_fp8_sdwa v[194:195], v70 src0_sel:WORD_1
	v_cvt_pk_f32_fp8_e32 v[196:197], v71
	v_pk_fma_f32 v[192:193], v[192:193], v[154:155], 0 op_sel_hi:[1,0,0]
	v_cvt_pk_f32_fp8_sdwa v[70:71], v71 src0_sel:WORD_1
	v_pk_fma_f32 v[192:193], v[204:205], v[154:155], v[192:193] op_sel:[0,1,0]
	v_cvt_pk_f32_fp8_sdwa v[204:205], v74 src0_sel:WORD_1
	v_pk_fma_f32 v[194:195], v[194:195], v[154:155], 0 op_sel_hi:[1,0,0]
	v_pk_fma_f32 v[70:71], v[70:71], v[154:155], 0 op_sel_hi:[1,0,0]
	v_cvt_pk_f32_fp8_e32 v[198:199], v72
	v_pk_fma_f32 v[194:195], v[204:205], v[154:155], v[194:195] op_sel:[0,1,0]
	v_cvt_pk_f32_fp8_e32 v[204:205], v75
	v_cvt_pk_f32_fp8_sdwa v[74:75], v75 src0_sel:WORD_1
	v_pk_fma_f32 v[198:199], v[198:199], v[154:155], 0 op_sel_hi:[1,0,0]
	v_cvt_pk_f32_fp8_sdwa v[200:201], v72 src0_sel:WORD_1
	v_cvt_pk_f32_fp8_e32 v[202:203], v73
	v_pk_fma_f32 v[74:75], v[74:75], v[154:155], v[70:71] op_sel:[0,1,0]
	v_cvt_pk_f32_fp8_e32 v[70:71], v76
	v_pk_fma_f32 v[200:201], v[200:201], v[154:155], 0 op_sel_hi:[1,0,0]
	v_cvt_pk_f32_fp8_sdwa v[72:73], v73 src0_sel:WORD_1
	v_pk_fma_f32 v[196:197], v[196:197], v[154:155], 0 op_sel_hi:[1,0,0]
	v_pk_fma_f32 v[70:71], v[70:71], v[154:155], v[198:199] op_sel:[0,1,0]
	v_cvt_pk_f32_fp8_sdwa v[198:199], v76 src0_sel:WORD_1
	v_pk_fma_f32 v[202:203], v[202:203], v[154:155], 0 op_sel_hi:[1,0,0]
	v_pk_fma_f32 v[72:73], v[72:73], v[154:155], 0 op_sel_hi:[1,0,0]
	v_pk_fma_f32 v[196:197], v[204:205], v[154:155], v[196:197] op_sel:[0,1,0]
	v_pk_fma_f32 v[198:199], v[198:199], v[154:155], v[200:201] op_sel:[0,1,0]
	v_cvt_pk_f32_fp8_e32 v[200:201], v77
	v_cvt_pk_f32_fp8_sdwa v[76:77], v77 src0_sel:WORD_1
	v_pk_fma_f32 v[200:201], v[200:201], v[154:155], v[202:203] op_sel:[0,1,0]
; __device__ __forceinline__ f32x2 fp8x2_lo(unsigned w) { return __builtin_amdgcn_cvt_pk_f32_fp8(w, false); }
; __device__ __forceinline__ f32x2 fp8x2_hi(unsigned w) { return __builtin_amdgcn_cvt_pk_f32_fp8(w, true); }
; template <bool NT>
; __device__ __forceinline__ void peer_passB(const Args& a, const PeerWork w) {
;     ...
;         for (int k = 0; k < 16; ++k) {
;             const unsigned ww[4] = {vr[k].x, vr[k].y, vr[k].z, vr[k].w};
;             const float c = cf[k >> 2][k & 3]; const f32x2 c2 = {c, c};
; #pragma unroll
;             for (int wd = 0; wd < 4; ++wd) { acc[2 * wd] = __builtin_elementwise_fma(fp8x2_lo(ww[wd]), c2, acc[2 * wd]); acc[2 * wd + 1] = __builtin_elementwise_fma(fp8x2_hi(ww[wd]), c2, acc[2 * wd + 1]); }
	v_pk_fma_f32 v[154:155], v[76:77], v[154:155], v[72:73] op_sel:[0,1,0]
	v_cvt_pk_f32_fp8_e32 v[76:77], v78
	v_cvt_pk_f32_fp8_sdwa v[72:73], v78 src0_sel:WORD_1
	v_pk_fma_f32 v[76:77], v[76:77], v[156:157], v[192:193] op_sel_hi:[1,0,1]
	v_cvt_pk_f32_fp8_e32 v[192:193], v79
	v_cvt_pk_f32_fp8_sdwa v[78:79], v79 src0_sel:WORD_1
	v_pk_fma_f32 v[72:73], v[72:73], v[156:157], v[194:195] op_sel_hi:[1,0,1]
	v_cvt_pk_f32_fp8_e32 v[194:195], v81
	v_pk_fma_f32 v[192:193], v[192:193], v[156:157], v[196:197] op_sel_hi:[1,0,1]
	v_pk_fma_f32 v[78:79], v[78:79], v[156:157], v[74:75] op_sel_hi:[1,0,1]
	v_cvt_pk_f32_fp8_e32 v[74:75], v80
	v_pk_fma_f32 v[194:195], v[194:195], v[156:157], v[200:201] op_sel_hi:[1,0,1]
	v_pk_fma_f32 v[74:75], v[74:75], v[156:157], v[70:71] op_sel_hi:[1,0,1]
	v_cvt_pk_f32_fp8_sdwa v[70:71], v80 src0_sel:WORD_1
	v_cvt_pk_f32_fp8_sdwa v[80:81], v81 src0_sel:WORD_1
	v_pk_fma_f32 v[70:71], v[70:71], v[156:157], v[198:199] op_sel_hi:[1,0,1]
	v_pk_fma_f32 v[154:155], v[80:81], v[156:157], v[154:155] op_sel_hi:[1,0,1]
	v_cvt_pk_f32_fp8_e32 v[80:81], v82
	v_mov_b32_e32 v156, v157
	v_pk_fma_f32 v[80:81], v[80:81], v[156:157], v[76:77] op_sel_hi:[1,0,1]
	v_cvt_pk_f32_fp8_sdwa v[76:77], v82 src0_sel:WORD_1
	v_pk_fma_f32 v[76:77], v[76:77], v[156:157], v[72:73] op_sel_hi:[1,0,1]
	v_cvt_pk_f32_fp8_e32 v[72:73], v83
	v_cvt_pk_f32_fp8_sdwa v[82:83], v83 src0_sel:WORD_1
	v_pk_fma_f32 v[72:73], v[72:73], v[156:157], v[192:193] op_sel_hi:[1,0,1]
	v_pk_fma_f32 v[82:83], v[82:83], v[156:157], v[78:79] op_sel_hi:[1,0,1]
	v_cvt_pk_f32_fp8_e32 v[78:79], v84
	v_pk_fma_f32 v[78:79], v[78:79], v[156:157], v[74:75] op_sel_hi:[1,0,1]
	v_cvt_pk_f32_fp8_sdwa v[74:75], v84 src0_sel:WORD_1
	v_pk_fma_f32 v[74:75], v[74:75], v[156:157], v[70:71] op_sel_hi:[1,0,1]
	v_cvt_pk_f32_fp8_e32 v[70:71], v85
	v_cvt_pk_f32_fp8_sdwa v[84:85], v85 src0_sel:WORD_1
	v_pk_fma_f32 v[70:71], v[70:71], v[156:157], v[194:195] op_sel_hi:[1,0,1]
	v_pk_fma_f32 v[84:85], v[84:85], v[156:157], v[154:155] op_sel_hi:[1,0,1]
	v_cvt_pk_f32_fp8_e32 v[154:155], v86
	v_cvt_pk_f32_fp8_sdwa v[156:157], v86 src0_sel:WORD_1
	v_pk_fma_f32 v[154:155], v[154:155], v[150:151], v[80:81] op_sel_hi:[1,0,1]
	v_cvt_pk_f32_fp8_e32 v[80:81], v87
	v_cvt_pk_f32_fp8_sdwa v[86:87], v87 src0_sel:WORD_1
	v_pk_fma_f32 v[156:157], v[156:157], v[150:151], v[76:77] op_sel_hi:[1,0,1]
	v_pk_fma_f32 v[80:81], v[80:81], v[150:151], v[72:73] op_sel_hi:[1,0,1]
	v_pk_fma_f32 v[86:87], v[86:87], v[150:151], v[82:83] op_sel_hi:[1,0,1]
	v_cvt_pk_f32_fp8_e32 v[82:83], v88
	v_pk_fma_f32 v[82:83], v[82:83], v[150:151], v[78:79] op_sel_hi:[1,0,1]
	v_cvt_pk_f32_fp8_sdwa v[78:79], v88 src0_sel:WORD_1
	v_pk_fma_f32 v[78:79], v[78:79], v[150:151], v[74:75] op_sel_hi:[1,0,1]
	v_cvt_pk_f32_fp8_e32 v[74:75], v89
	v_cvt_pk_f32_fp8_sdwa v[88:89], v89 src0_sel:WORD_1
	v_pk_fma_f32 v[74:75], v[74:75], v[150:151], v[70:71] op_sel_hi:[1,0,1]
	v_pk_fma_f32 v[88:89], v[88:89], v[150:151], v[84:85] op_sel_hi:[1,0,1]
	v_cvt_pk_f32_fp8_e32 v[84:85], v90
	v_pk_fma_f32 v[84:85], v[84:85], v[150:151], v[154:155] op_sel:[0,1,0]
	v_cvt_pk_f32_fp8_sdwa v[154:155], v90 src0_sel:WORD_1
	v_pk_fma_f32 v[154:155], v[154:155], v[150:151], v[156:157] op_sel:[0,1,0]
	v_cvt_pk_f32_fp8_e32 v[156:157], v91
	v_cvt_pk_f32_fp8_sdwa v[90:91], v91 src0_sel:WORD_1
	s_ashr_i32 s13, s12, 31
	v_pk_fma_f32 v[156:157], v[156:157], v[150:151], v[80:81] op_sel:[0,1,0]
	v_pk_fma_f32 v[90:91], v[90:91], v[150:151], v[86:87] op_sel:[0,1,0]
	v_cvt_pk_f32_fp8_e32 v[86:87], v92
	s_lshl_b64 s[12:13], s[12:13], 12
	s_add_i32 s18, s18, s22
	v_pk_fma_f32 v[86:87], v[86:87], v[150:151], v[82:83] op_sel:[0,1,0]
	v_cvt_pk_f32_fp8_sdwa v[82:83], v92 src0_sel:WORD_1
	s_cmpk_lt_i32 s18, 0x4000
	v_pk_fma_f32 v[82:83], v[82:83], v[150:151], v[78:79] op_sel:[0,1,0]
	v_cvt_pk_f32_fp8_e32 v[78:79], v93
	v_cvt_pk_f32_fp8_sdwa v[92:93], v93 src0_sel:WORD_1
	v_pk_fma_f32 v[78:79], v[78:79], v[150:151], v[74:75] op_sel:[0,1,0]
	v_pk_fma_f32 v[150:151], v[92:93], v[150:151], v[88:89] op_sel:[0,1,0]
	v_cvt_pk_f32_fp8_e32 v[92:93], v98
	v_cvt_pk_f32_fp8_sdwa v[88:89], v98 src0_sel:WORD_1
	v_pk_fma_f32 v[92:93], v[92:93], v[152:153], v[84:85] op_sel_hi:[1,0,1]
	v_cvt_pk_f32_fp8_e32 v[84:85], v99
	v_cvt_pk_f32_fp8_sdwa v[98:99], v99 src0_sel:WORD_1
	v_pk_fma_f32 v[88:89], v[88:89], v[152:153], v[154:155] op_sel_hi:[1,0,1]
	v_pk_fma_f32 v[84:85], v[84:85], v[152:153], v[156:157] op_sel_hi:[1,0,1]
	v_pk_fma_f32 v[98:99], v[98:99], v[152:153], v[90:91] op_sel_hi:[1,0,1]
	v_cvt_pk_f32_fp8_e32 v[90:91], v100
	v_pk_fma_f32 v[90:91], v[90:91], v[152:153], v[86:87] op_sel_hi:[1,0,1]
	v_cvt_pk_f32_fp8_sdwa v[86:87], v100 src0_sel:WORD_1
	v_pk_fma_f32 v[86:87], v[86:87], v[152:153], v[82:83] op_sel_hi:[1,0,1]
	v_cvt_pk_f32_fp8_e32 v[82:83], v101
	v_cvt_pk_f32_fp8_sdwa v[100:101], v101 src0_sel:WORD_1
	v_pk_fma_f32 v[82:83], v[82:83], v[152:153], v[78:79] op_sel_hi:[1,0,1]
	v_pk_fma_f32 v[150:151], v[100:101], v[152:153], v[150:151] op_sel_hi:[1,0,1]
	v_cvt_pk_f32_fp8_e32 v[100:101], v102
	v_mov_b32_e32 v152, v153
	v_pk_fma_f32 v[100:101], v[100:101], v[152:153], v[92:93] op_sel_hi:[1,0,1]
	v_cvt_pk_f32_fp8_sdwa v[92:93], v102 src0_sel:WORD_1
	v_pk_fma_f32 v[92:93], v[92:93], v[152:153], v[88:89] op_sel_hi:[1,0,1]
	v_cvt_pk_f32_fp8_e32 v[88:89], v103
	v_cvt_pk_f32_fp8_sdwa v[102:103], v103 src0_sel:WORD_1
	v_pk_fma_f32 v[88:89], v[88:89], v[152:153], v[84:85] op_sel_hi:[1,0,1]
	v_pk_fma_f32 v[102:103], v[102:103], v[152:153], v[98:99] op_sel_hi:[1,0,1]
	v_cvt_pk_f32_fp8_e32 v[98:99], v104
	v_pk_fma_f32 v[98:99], v[98:99], v[152:153], v[90:91] op_sel_hi:[1,0,1]
	v_cvt_pk_f32_fp8_sdwa v[90:91], v104 src0_sel:WORD_1
; __device__ __forceinline__ f32x2 fp8x2_lo(unsigned w) { return __builtin_amdgcn_cvt_pk_f32_fp8(w, false); }
; __device__ __forceinline__ f32x2 fp8x2_hi(unsigned w) { return __builtin_amdgcn_cvt_pk_f32_fp8(w, true); }
; template <bool NT>
; __device__ __forceinline__ void peer_passB(const Args& a, const PeerWork w) {
;     ...
;         for (int k = 0; k < 16; ++k) {
;             const unsigned ww[4] = {vr[k].x, vr[k].y, vr[k].z, vr[k].w};
;             const float c = cf[k >> 2][k & 3]; const f32x2 c2 = {c, c};
; #pragma unroll
;             for (int wd = 0; wd < 4; ++wd) { acc[2 * wd] = __builtin_elementwise_fma(fp8x2_lo(ww[wd]), c2, acc[2 * wd]); acc[2 * wd + 1] = __builtin_elementwise_fma(fp8x2_hi(ww[wd]), c2, acc[2 * wd + 1]); }
	v_pk_fma_f32 v[90:91], v[90:91], v[152:153], v[86:87] op_sel_hi:[1,0,1]
	v_cvt_pk_f32_fp8_e32 v[86:87], v105
	v_cvt_pk_f32_fp8_sdwa v[104:105], v105 src0_sel:WORD_1
	v_pk_fma_f32 v[86:87], v[86:87], v[152:153], v[82:83] op_sel_hi:[1,0,1]
	v_pk_fma_f32 v[104:105], v[104:105], v[152:153], v[150:151] op_sel_hi:[1,0,1]
	v_cvt_pk_f32_fp8_e32 v[150:151], v106
	v_cvt_pk_f32_fp8_sdwa v[152:153], v106 src0_sel:WORD_1
	v_pk_fma_f32 v[150:151], v[150:151], v[146:147], v[100:101] op_sel_hi:[1,0,1]
	v_cvt_pk_f32_fp8_e32 v[100:101], v107
	v_cvt_pk_f32_fp8_sdwa v[106:107], v107 src0_sel:WORD_1
	v_pk_fma_f32 v[152:153], v[152:153], v[146:147], v[92:93] op_sel_hi:[1,0,1]
	v_pk_fma_f32 v[100:101], v[100:101], v[146:147], v[88:89] op_sel_hi:[1,0,1]
	v_pk_fma_f32 v[106:107], v[106:107], v[146:147], v[102:103] op_sel_hi:[1,0,1]
	v_cvt_pk_f32_fp8_e32 v[102:103], v108
	v_pk_fma_f32 v[102:103], v[102:103], v[146:147], v[98:99] op_sel_hi:[1,0,1]
	v_cvt_pk_f32_fp8_sdwa v[98:99], v108 src0_sel:WORD_1
	v_pk_fma_f32 v[98:99], v[98:99], v[146:147], v[90:91] op_sel_hi:[1,0,1]
	v_cvt_pk_f32_fp8_e32 v[90:91], v109
	v_cvt_pk_f32_fp8_sdwa v[108:109], v109 src0_sel:WORD_1
	v_pk_fma_f32 v[90:91], v[90:91], v[146:147], v[86:87] op_sel_hi:[1,0,1]
	v_pk_fma_f32 v[108:109], v[108:109], v[146:147], v[104:105] op_sel_hi:[1,0,1]
	v_cvt_pk_f32_fp8_e32 v[104:105], v110
	v_pk_fma_f32 v[104:105], v[104:105], v[146:147], v[150:151] op_sel:[0,1,0]
	v_cvt_pk_f32_fp8_sdwa v[150:151], v110 src0_sel:WORD_1
	v_pk_fma_f32 v[150:151], v[150:151], v[146:147], v[152:153] op_sel:[0,1,0]
	v_cvt_pk_f32_fp8_e32 v[152:153], v111
	v_cvt_pk_f32_fp8_sdwa v[110:111], v111 src0_sel:WORD_1
	v_pk_fma_f32 v[152:153], v[152:153], v[146:147], v[100:101] op_sel:[0,1,0]
	v_pk_fma_f32 v[110:111], v[110:111], v[146:147], v[106:107] op_sel:[0,1,0]
	v_cvt_pk_f32_fp8_e32 v[106:107], v112
	v_pk_fma_f32 v[106:107], v[106:107], v[146:147], v[102:103] op_sel:[0,1,0]
	v_cvt_pk_f32_fp8_sdwa v[102:103], v112 src0_sel:WORD_1
	v_pk_fma_f32 v[102:103], v[102:103], v[146:147], v[98:99] op_sel:[0,1,0]
	v_cvt_pk_f32_fp8_e32 v[98:99], v113
	v_cvt_pk_f32_fp8_sdwa v[112:113], v113 src0_sel:WORD_1
	v_pk_fma_f32 v[98:99], v[98:99], v[146:147], v[90:91] op_sel:[0,1,0]
	v_pk_fma_f32 v[146:147], v[112:113], v[146:147], v[108:109] op_sel:[0,1,0]
	v_cvt_pk_f32_fp8_e32 v[112:113], v114
	v_cvt_pk_f32_fp8_sdwa v[108:109], v114 src0_sel:WORD_1
	v_pk_fma_f32 v[112:113], v[112:113], v[148:149], v[104:105] op_sel_hi:[1,0,1]
	v_cvt_pk_f32_fp8_e32 v[104:105], v115
	v_cvt_pk_f32_fp8_sdwa v[114:115], v115 src0_sel:WORD_1
	v_pk_fma_f32 v[108:109], v[108:109], v[148:149], v[150:151] op_sel_hi:[1,0,1]
	v_pk_fma_f32 v[104:105], v[104:105], v[148:149], v[152:153] op_sel_hi:[1,0,1]
	v_pk_fma_f32 v[114:115], v[114:115], v[148:149], v[110:111] op_sel_hi:[1,0,1]
	v_cvt_pk_f32_fp8_e32 v[110:111], v116
	v_pk_fma_f32 v[110:111], v[110:111], v[148:149], v[106:107] op_sel_hi:[1,0,1]
	v_cvt_pk_f32_fp8_sdwa v[106:107], v116 src0_sel:WORD_1
	v_pk_fma_f32 v[106:107], v[106:107], v[148:149], v[102:103] op_sel_hi:[1,0,1]
	v_cvt_pk_f32_fp8_e32 v[102:103], v117
	v_cvt_pk_f32_fp8_sdwa v[116:117], v117 src0_sel:WORD_1
	v_pk_fma_f32 v[102:103], v[102:103], v[148:149], v[98:99] op_sel_hi:[1,0,1]
	v_pk_fma_f32 v[146:147], v[116:117], v[148:149], v[146:147] op_sel_hi:[1,0,1]
	v_cvt_pk_f32_fp8_e32 v[116:117], v118
	v_mov_b32_e32 v148, v149
	v_pk_fma_f32 v[116:117], v[116:117], v[148:149], v[112:113] op_sel_hi:[1,0,1]
	v_cvt_pk_f32_fp8_sdwa v[112:113], v118 src0_sel:WORD_1
	v_pk_fma_f32 v[112:113], v[112:113], v[148:149], v[108:109] op_sel_hi:[1,0,1]
	v_cvt_pk_f32_fp8_e32 v[108:109], v119
	v_cvt_pk_f32_fp8_sdwa v[118:119], v119 src0_sel:WORD_1
	v_pk_fma_f32 v[108:109], v[108:109], v[148:149], v[104:105] op_sel_hi:[1,0,1]
	v_pk_fma_f32 v[118:119], v[118:119], v[148:149], v[114:115] op_sel_hi:[1,0,1]
	v_cvt_pk_f32_fp8_e32 v[114:115], v120
	v_pk_fma_f32 v[114:115], v[114:115], v[148:149], v[110:111] op_sel_hi:[1,0,1]
	v_cvt_pk_f32_fp8_sdwa v[110:111], v120 src0_sel:WORD_1
	v_pk_fma_f32 v[110:111], v[110:111], v[148:149], v[106:107] op_sel_hi:[1,0,1]
	v_cvt_pk_f32_fp8_e32 v[106:107], v121
	v_cvt_pk_f32_fp8_sdwa v[120:121], v121 src0_sel:WORD_1
	v_pk_fma_f32 v[106:107], v[106:107], v[148:149], v[102:103] op_sel_hi:[1,0,1]
	v_pk_fma_f32 v[146:147], v[120:121], v[148:149], v[146:147] op_sel_hi:[1,0,1]
	v_cvt_pk_f32_fp8_e32 v[148:149], v122
	v_cvt_pk_f32_fp8_sdwa v[120:121], v122 src0_sel:WORD_1
	v_pk_fma_f32 v[148:149], v[148:149], v[142:143], v[116:117] op_sel_hi:[1,0,1]
	v_cvt_pk_f32_fp8_e32 v[116:117], v123
	v_cvt_pk_f32_fp8_sdwa v[122:123], v123 src0_sel:WORD_1
	v_pk_fma_f32 v[120:121], v[120:121], v[142:143], v[112:113] op_sel_hi:[1,0,1]
	v_pk_fma_f32 v[116:117], v[116:117], v[142:143], v[108:109] op_sel_hi:[1,0,1]
	v_pk_fma_f32 v[122:123], v[122:123], v[142:143], v[118:119] op_sel_hi:[1,0,1]
	v_cvt_pk_f32_fp8_e32 v[118:119], v124
; template <int CTRL> __device__ __forceinline__ float dpp_f(float x) { return __uint_as_float((unsigned)__builtin_amdgcn_update_dpp(0, (int)__float_as_uint(x), CTRL, 0xf, 0xf, false)); }
; __device__ __forceinline__ f32x2 fp8x2_lo(unsigned w) { return __builtin_amdgcn_cvt_pk_f32_fp8(w, false); }
; __device__ __forceinline__ f32x2 fp8x2_hi(unsigned w) { return __builtin_amdgcn_cvt_pk_f32_fp8(w, true); }
; template <bool NT>
; __device__ __forceinline__ void peer_passB(const Args& a, const PeerWork w) {
;     ...
;         for (int k = 0; k < 16; ++k) {
;             const unsigned ww[4] = {vr[k].x, vr[k].y, vr[k].z, vr[k].w};
;             const float c = cf[k >> 2][k & 3]; const f32x2 c2 = {c, c};
; #pragma unroll
;             for (int wd = 0; wd < 4; ++wd) { acc[2 * wd] = __builtin_elementwise_fma(fp8x2_lo(ww[wd]), c2, acc[2 * wd]); acc[2 * wd + 1] = __builtin_elementwise_fma(fp8x2_hi(ww[wd]), c2, acc[2 * wd + 1]); }
;         }
;         float w8[8], w4[4], w2[2];
; #pragma unroll
;         for (int m = 0; m < 8; ++m) { const auto sw = __builtin_amdgcn_permlane32_swap(__float_as_uint(acc[m >> 1][m & 1]), __float_as_uint(acc[(m + 8) >> 1][m & 1]), false, false); w8[m] = __uint_as_float(sw[0]) + __uint_as_float(sw[1]); }
; #pragma unroll
;         for (int m = 0; m < 4; ++m) { const auto sw = __builtin_amdgcn_permlane16_swap(__float_as_uint(w8[m]), __float_as_uint(w8[m + 4]), false, false); w4[m] = __uint_as_float(sw[0]) + __uint_as_float(sw[1]); }
;         { const bool up = (lane & 8) != 0;
; #pragma unroll
;           for (int m = 0; m < 2; ++m) { const float keep = up ? w4[m + 2] : w4[m], send = up ? w4[m] : w4[m + 2]; w2[m] = keep + dpp_f<0x128>(send); } }
;         *(f32x2*)(Y + (size_t)t * DM) = (f32x2){hv[0] + w2[0], hv[1] + w2[1]};
;         if (q + qs > ql) break;
; #pragma unroll
;         for (int k = 0; k < 16; ++k) vr[k] = vrn[k];
; #pragma unroll
;         for (int qq = 0; qq < 4; ++qq) cf[qq] = cfn[qq];
;         hv = hn;
;         t = t1; t1 = t2;
	v_pk_fma_f32 v[118:119], v[118:119], v[142:143], v[114:115] op_sel_hi:[1,0,1]
	v_cvt_pk_f32_fp8_sdwa v[114:115], v124 src0_sel:WORD_1
	v_pk_fma_f32 v[114:115], v[114:115], v[142:143], v[110:111] op_sel_hi:[1,0,1]
	v_cvt_pk_f32_fp8_e32 v[110:111], v125
	v_cvt_pk_f32_fp8_sdwa v[124:125], v125 src0_sel:WORD_1
	v_pk_fma_f32 v[110:111], v[110:111], v[142:143], v[106:107] op_sel_hi:[1,0,1]
	v_pk_fma_f32 v[124:125], v[124:125], v[142:143], v[146:147] op_sel_hi:[1,0,1]
	v_cvt_pk_f32_fp8_e32 v[146:147], v126
	v_pk_fma_f32 v[146:147], v[146:147], v[142:143], v[148:149] op_sel:[0,1,0]
	v_cvt_pk_f32_fp8_sdwa v[148:149], v126 src0_sel:WORD_1
	v_pk_fma_f32 v[148:149], v[148:149], v[142:143], v[120:121] op_sel:[0,1,0]
	v_cvt_pk_f32_fp8_e32 v[120:121], v127
	v_cvt_pk_f32_fp8_sdwa v[126:127], v127 src0_sel:WORD_1
	v_pk_fma_f32 v[120:121], v[120:121], v[142:143], v[116:117] op_sel:[0,1,0]
	v_pk_fma_f32 v[126:127], v[126:127], v[142:143], v[122:123] op_sel:[0,1,0]
	v_cvt_pk_f32_fp8_e32 v[122:123], v128
	v_pk_fma_f32 v[122:123], v[122:123], v[142:143], v[118:119] op_sel:[0,1,0]
	v_cvt_pk_f32_fp8_sdwa v[118:119], v128 src0_sel:WORD_1
	v_pk_fma_f32 v[118:119], v[118:119], v[142:143], v[114:115] op_sel:[0,1,0]
	v_cvt_pk_f32_fp8_e32 v[114:115], v129
	v_cvt_pk_f32_fp8_sdwa v[128:129], v129 src0_sel:WORD_1
	v_pk_fma_f32 v[114:115], v[114:115], v[142:143], v[110:111] op_sel:[0,1,0]
	v_pk_fma_f32 v[142:143], v[128:129], v[142:143], v[124:125] op_sel:[0,1,0]
	v_cvt_pk_f32_fp8_e32 v[128:129], v130
	v_cvt_pk_f32_fp8_sdwa v[124:125], v130 src0_sel:WORD_1
	v_pk_fma_f32 v[128:129], v[128:129], v[144:145], v[146:147] op_sel_hi:[1,0,1]
	v_cvt_pk_f32_fp8_e32 v[146:147], v131
	v_cvt_pk_f32_fp8_sdwa v[130:131], v131 src0_sel:WORD_1
	v_pk_fma_f32 v[124:125], v[124:125], v[144:145], v[148:149] op_sel_hi:[1,0,1]
	v_cvt_pk_f32_fp8_e32 v[148:149], v133
	v_pk_fma_f32 v[146:147], v[146:147], v[144:145], v[120:121] op_sel_hi:[1,0,1]
	v_pk_fma_f32 v[130:131], v[130:131], v[144:145], v[126:127] op_sel_hi:[1,0,1]
	v_cvt_pk_f32_fp8_e32 v[126:127], v132
	v_pk_fma_f32 v[148:149], v[148:149], v[144:145], v[114:115] op_sel_hi:[1,0,1]
	v_pk_fma_f32 v[126:127], v[126:127], v[144:145], v[122:123] op_sel_hi:[1,0,1]
	v_cvt_pk_f32_fp8_sdwa v[122:123], v132 src0_sel:WORD_1
	v_cvt_pk_f32_fp8_sdwa v[132:133], v133 src0_sel:WORD_1
	v_pk_fma_f32 v[122:123], v[122:123], v[144:145], v[118:119] op_sel_hi:[1,0,1]
	v_pk_fma_f32 v[142:143], v[132:133], v[144:145], v[142:143] op_sel_hi:[1,0,1]
	v_cvt_pk_f32_fp8_e32 v[132:133], v134
	v_mov_b32_e32 v144, v145
	v_pk_fma_f32 v[132:133], v[132:133], v[144:145], v[128:129] op_sel_hi:[1,0,1]
	v_cvt_pk_f32_fp8_sdwa v[128:129], v134 src0_sel:WORD_1
	v_pk_fma_f32 v[128:129], v[128:129], v[144:145], v[124:125] op_sel_hi:[1,0,1]
	v_cvt_pk_f32_fp8_e32 v[124:125], v135
	v_cvt_pk_f32_fp8_sdwa v[134:135], v135 src0_sel:WORD_1
	v_pk_fma_f32 v[124:125], v[124:125], v[144:145], v[146:147] op_sel_hi:[1,0,1]
	v_pk_fma_f32 v[134:135], v[134:135], v[144:145], v[130:131] op_sel_hi:[1,0,1]
	v_cvt_pk_f32_fp8_e32 v[130:131], v136
	v_pk_fma_f32 v[130:131], v[130:131], v[144:145], v[126:127] op_sel_hi:[1,0,1]
	v_cvt_pk_f32_fp8_sdwa v[126:127], v136 src0_sel:WORD_1
	s_nop 0
	v_permlane32_swap_b32_e32 v132, v130
	v_permlane32_swap_b32_e32 v133, v131
	v_pk_fma_f32 v[126:127], v[126:127], v[144:145], v[122:123] op_sel_hi:[1,0,1]
	v_cvt_pk_f32_fp8_e32 v[122:123], v137
	v_cvt_pk_f32_fp8_sdwa v[136:137], v137 src0_sel:WORD_1
	v_permlane32_swap_b32_e32 v128, v126
	v_pk_fma_f32 v[122:123], v[122:123], v[144:145], v[148:149] op_sel_hi:[1,0,1]
	v_pk_fma_f32 v[136:137], v[136:137], v[144:145], v[142:143] op_sel_hi:[1,0,1]
	v_permlane32_swap_b32_e32 v129, v127
	v_permlane32_swap_b32_e32 v124, v122
	v_permlane32_swap_b32_e32 v125, v123
	v_permlane32_swap_b32_e32 v134, v136
	v_permlane32_swap_b32_e32 v135, v137
	v_add_f32_e32 v142, v132, v130
	v_add_f32_e32 v143, v133, v131
	v_add_f32_e32 v144, v128, v126
	v_add_f32_e32 v145, v129, v127
	v_add_f32_e32 v130, v124, v122
	v_add_f32_e32 v131, v125, v123
	v_add_f32_e32 v134, v134, v136
	v_add_f32_e32 v135, v135, v137
	v_permlane16_swap_b32_e32 v142, v130
	v_permlane16_swap_b32_e32 v143, v131
	v_permlane16_swap_b32_e32 v144, v134
	v_permlane16_swap_b32_e32 v145, v135
	v_pk_add_f32 v[136:137], v[142:143], v[130:131]
	v_pk_add_f32 v[134:135], v[144:145], v[134:135]
	v_mov_b32_e32 v142, 0
	v_cndmask_b32_e32 v143, v136, v134, vcc
	v_cndmask_b32_e32 v144, v134, v136, vcc
	v_cndmask_b32_e32 v134, v137, v135, vcc
	v_mov_b32_dpp v142, v143 row_ror:8 row_mask:0xf bank_mask:0xf
	v_mov_b32_e32 v143, 0
	v_cndmask_b32_e32 v145, v135, v137, vcc
	v_lshl_add_u64 v[136:137], v[186:187], 0, s[12:13]
	v_mov_b32_dpp v143, v134 row_ror:8 row_mask:0xf bank_mask:0xf
	v_pk_add_f32 v[134:135], v[144:145], v[142:143]
	v_pk_add_f32 v[134:135], v[188:189], v[134:135]
	global_store_dwordx2 v[136:137], v[134:135], off
	s_mov_b32 s12, s14
	s_cbranch_scc1 .LBB0_1587
	s_waitcnt vmcnt(0)
